# grid barrier: the globally last arriver increments every XCD's generation word itself (16 fire-and-forget atomics); XCD leaders no longer relay it - one hop less for non-leader workgroups (on top of v
# speedup vs baseline: 1.0145x; 1.0004x over previous
; DI unsigned xb_ld(unsigned* p)              { return __hip_atomic_load(p, __ATOMIC_RELAXED, __HIP_MEMORY_SCOPE_AGENT); }
; DI unsigned xb_add(unsigned* p, unsigned v) { return __hip_atomic_fetch_add(p, v, __ATOMIC_RELAXED, __HIP_MEMORY_SCOPE_AGENT); }
; #define XB_SPIN(cond, bar) do { unsigned _sp = 0; while (cond) { __builtin_amdgcn_s_sleep(1); \
;     if ((++_sp & 255u) == 0u) { if (xb_ld(&(bar)[XB_TMO])) break; if (_sp > XB_SPIN_CAP) { atomicAdd(&(bar)[XB_TMO], 1u); break; } } } } while (0)
; DI void xcd_barrier(const XcdBarrier& b) {
;     ...
;         const unsigned old = xb_add(&bar[XB_XSUB(b.x)], 1u);
;         const unsigned gen = old / nloc;
;         if (old + 1u == (gen + 1u) * nloc) {
;             __builtin_amdgcn_fence(__ATOMIC_RELEASE, "agent");
;             asm volatile("s_waitcnt vmcnt(0)" ::: "memory");
;             const unsigned og = xb_add(&bar[XB_TOP], 1u);
;             const unsigned tg = og / nx;
;             if (og + 1u == (tg + 1u) * nx) xb_add(&bar[XB_TOPGEN], 1u);
;             else XB_SPIN(xb_ld(&bar[XB_TOPGEN]) == tg, bar);
;             __builtin_amdgcn_fence(__ATOMIC_ACQUIRE, "agent");
;             xb_add(&bar[XB_XGEN(b.x)], 1u);
.LBB0_270:
	s_or_b64 exec, exec, s[6:7]
	v_cvt_f32_u32_e32 v6, v3
	s_waitcnt vmcnt(0)
	v_readfirstlane_b32 s4, v5
	v_sub_u32_e32 v5, 0, v3
	s_mov_b64 s[6:7], -1
	v_rcp_iflag_f32_e32 v6, v6
	v_add_u32_e32 v4, s4, v4
	v_add_u32_e32 v7, 1, v4
	v_readlane_b32 s4, v253, 52
	v_mul_f32_e32 v6, 0x4f7ffffe, v6
	v_cvt_u32_f32_e32 v6, v6
	v_readlane_b32 s5, v253, 53
	v_mul_lo_u32 v5, v5, v6
	v_mul_hi_u32 v5, v6, v5
	v_add_u32_e32 v5, v6, v5
	v_mul_hi_u32 v5, v4, v5
	v_mul_lo_u32 v6, v5, v3
	v_sub_u32_e32 v4, v4, v6
	v_add_u32_e32 v8, 1, v5
	v_sub_u32_e32 v6, v4, v3
	v_cmp_ge_u32_e32 vcc, v4, v3
	s_nop 1
	v_cndmask_b32_e32 v5, v5, v8, vcc
	v_cndmask_b32_e32 v4, v4, v6, vcc
	v_add_u32_e32 v6, 1, v5
	v_cmp_ge_u32_e32 vcc, v4, v3
	s_nop 1
	v_cndmask_b32_e32 v6, v5, v6, vcc
	v_mul_lo_u32 v4, v3, v6
	v_add_u32_e32 v3, v4, v3
	v_cmp_ne_u32_e32 vcc, v7, v3
	v_mov_b64_e32 v[4:5], s[4:5]
	s_cbranch_vccnz .Lxg_skip_13
	s_add_u32 s100, s74, 0x6400
	s_addc_u32 s101, s75, 0
	global_atomic_add v2, v197, s[100:101]
	global_atomic_add v2, v197, s[100:101] offset:256
	global_atomic_add v2, v197, s[100:101] offset:512
	global_atomic_add v2, v197, s[100:101] offset:768
	global_atomic_add v2, v197, s[100:101] offset:1024
	global_atomic_add v2, v197, s[100:101] offset:1280
	global_atomic_add v2, v197, s[100:101] offset:1536
	global_atomic_add v2, v197, s[100:101] offset:1792
	global_atomic_add v2, v197, s[100:101] offset:2048
	global_atomic_add v2, v197, s[100:101] offset:2304
	global_atomic_add v2, v197, s[100:101] offset:2560
	global_atomic_add v2, v197, s[100:101] offset:2816
	global_atomic_add v2, v197, s[100:101] offset:3072
	global_atomic_add v2, v197, s[100:101] offset:3328
	global_atomic_add v2, v197, s[100:101] offset:3584
	global_atomic_add v2, v197, s[100:101] offset:3840
.Lxg_skip_13:
	s_and_saveexec_b64 s[4:5], vcc
	s_cbranch_execz .LBB0_282
	v_readlane_b32 s6, v253, 52
	v_readlane_b32 s7, v253, 53
	s_mov_b64 s[8:9], 0
	s_nop 3
	global_load_dword v3, v2, s[6:7] sc1
	s_waitcnt vmcnt(0)
	v_cmp_eq_u32_e32 vcc, v3, v6
	s_and_saveexec_b64 s[6:7], vcc
	s_cbranch_execz .LBB0_281
	s_mov_b32 s19, 1
	s_branch .LBB0_274

; DI unsigned xb_add(unsigned* p, unsigned v) { return __hip_atomic_fetch_add(p, v, __ATOMIC_RELAXED, __HIP_MEMORY_SCOPE_AGENT); }
; DI void xcd_barrier(const XcdBarrier& b) {
;     ...
;             __builtin_amdgcn_fence(__ATOMIC_ACQUIRE, "agent");
;             xb_add(&bar[XB_XGEN(b.x)], 1u);
;             asm volatile("s_waitcnt vmcnt(0)" ::: "memory");
.LBB0_284:
	s_or_b64 exec, exec, s[4:5]
	s_mov_b64 s[4:5], exec
	v_mbcnt_lo_u32_b32 v3, s4, 0
	v_mbcnt_hi_u32_b32 v3, s5, v3
	v_cmp_eq_u32_e32 vcc, 0, v3
	s_waitcnt vmcnt(0)
	buffer_inv sc1
	s_and_saveexec_b64 s[6:7], vcc
	s_cbranch_execz .LBB0_286
	s_bcnt1_i32_b64 s4, s[4:5]
	v_mov_b32_e32 v3, s4
	v_readlane_b32 s4, v253, 48
	v_readlane_b32 s5, v253, 49
	s_nop 4
	s_nop 0

; DI unsigned xb_ld(unsigned* p)              { return __hip_atomic_load(p, __ATOMIC_RELAXED, __HIP_MEMORY_SCOPE_AGENT); }
; DI unsigned xb_add(unsigned* p, unsigned v) { return __hip_atomic_fetch_add(p, v, __ATOMIC_RELAXED, __HIP_MEMORY_SCOPE_AGENT); }
; #define XB_SPIN(cond, bar) do { unsigned _sp = 0; while (cond) { __builtin_amdgcn_s_sleep(1); \
;     if ((++_sp & 255u) == 0u) { if (xb_ld(&(bar)[XB_TMO])) break; if (_sp > XB_SPIN_CAP) { atomicAdd(&(bar)[XB_TMO], 1u); break; } } } } while (0)
; DI void xcd_barrier(const XcdBarrier& b) {
;     ...
;         const unsigned old = xb_add(&bar[XB_XSUB(b.x)], 1u);
;         const unsigned gen = old / nloc;
;         if (old + 1u == (gen + 1u) * nloc) {
;             __builtin_amdgcn_fence(__ATOMIC_RELEASE, "agent");
;             asm volatile("s_waitcnt vmcnt(0)" ::: "memory");
;             const unsigned og = xb_add(&bar[XB_TOP], 1u);
;             const unsigned tg = og / nx;
;             if (og + 1u == (tg + 1u) * nx) xb_add(&bar[XB_TOPGEN], 1u);
;             else XB_SPIN(xb_ld(&bar[XB_TOPGEN]) == tg, bar);
;             __builtin_amdgcn_fence(__ATOMIC_ACQUIRE, "agent");
;             xb_add(&bar[XB_XGEN(b.x)], 1u);
.LBB0_368:
	s_or_b64 exec, exec, s[6:7]
	s_waitcnt vmcnt(0)
	v_readfirstlane_b32 s4, v5
	v_sub_u32_e32 v6, 0, v4
	s_mov_b64 s[6:7], -1
	v_add_u32_e32 v5, s4, v3
	v_cvt_f32_u32_e32 v3, v4
	v_readlane_b32 s4, v253, 52
	v_readlane_b32 s5, v253, 53
	v_rcp_iflag_f32_e32 v3, v3
	s_nop 0
	v_mul_f32_e32 v3, 0x4f7ffffe, v3
	v_cvt_u32_f32_e32 v3, v3
	v_mul_lo_u32 v6, v6, v3
	v_mul_hi_u32 v6, v3, v6
	v_add_u32_e32 v3, v3, v6
	v_mul_hi_u32 v3, v5, v3
	v_mul_lo_u32 v6, v3, v4
	v_sub_u32_e32 v6, v5, v6
	v_cmp_ge_u32_e32 vcc, v6, v4
	v_add_u32_e32 v7, 1, v3
	v_add_u32_e32 v5, 1, v5
	v_cndmask_b32_e32 v3, v3, v7, vcc
	v_sub_u32_e32 v7, v6, v4
	v_cndmask_b32_e32 v6, v6, v7, vcc
	v_cmp_ge_u32_e32 vcc, v6, v4
	v_add_u32_e32 v6, 1, v3
	s_nop 0
	v_cndmask_b32_e32 v3, v3, v6, vcc
	v_mul_lo_u32 v6, v4, v3
	v_add_u32_e32 v4, v6, v4
	v_cmp_ne_u32_e32 vcc, v5, v4
	v_mov_b64_e32 v[4:5], s[4:5]
	s_cbranch_vccnz .Lxg_skip_12
	s_add_u32 s100, s74, 0x6400
	s_addc_u32 s101, s75, 0
	global_atomic_add v2, v197, s[100:101]
	global_atomic_add v2, v197, s[100:101] offset:256
	global_atomic_add v2, v197, s[100:101] offset:512
	global_atomic_add v2, v197, s[100:101] offset:768
	global_atomic_add v2, v197, s[100:101] offset:1024
	global_atomic_add v2, v197, s[100:101] offset:1280
	global_atomic_add v2, v197, s[100:101] offset:1536
	global_atomic_add v2, v197, s[100:101] offset:1792
	global_atomic_add v2, v197, s[100:101] offset:2048
	global_atomic_add v2, v197, s[100:101] offset:2304
	global_atomic_add v2, v197, s[100:101] offset:2560
	global_atomic_add v2, v197, s[100:101] offset:2816
	global_atomic_add v2, v197, s[100:101] offset:3072
	global_atomic_add v2, v197, s[100:101] offset:3328
	global_atomic_add v2, v197, s[100:101] offset:3584
	global_atomic_add v2, v197, s[100:101] offset:3840
.Lxg_skip_12:
	s_and_saveexec_b64 s[4:5], vcc
	s_cbranch_execz .LBB0_380
	v_readlane_b32 s6, v253, 52
	v_readlane_b32 s7, v253, 53
	s_mov_b64 s[8:9], 0
	s_nop 3
	global_load_dword v4, v2, s[6:7] sc1
	s_waitcnt vmcnt(0)
	v_cmp_eq_u32_e32 vcc, v4, v3
	s_and_saveexec_b64 s[6:7], vcc
	s_cbranch_execz .LBB0_379
	s_mov_b32 s19, 1
	s_branch .LBB0_372

; DI unsigned xb_ld(unsigned* p)              { return __hip_atomic_load(p, __ATOMIC_RELAXED, __HIP_MEMORY_SCOPE_AGENT); }
; DI unsigned xb_add(unsigned* p, unsigned v) { return __hip_atomic_fetch_add(p, v, __ATOMIC_RELAXED, __HIP_MEMORY_SCOPE_AGENT); }
; #define XB_SPIN(cond, bar) do { unsigned _sp = 0; while (cond) { __builtin_amdgcn_s_sleep(1); \
;     if ((++_sp & 255u) == 0u) { if (xb_ld(&(bar)[XB_TMO])) break; if (_sp > XB_SPIN_CAP) { atomicAdd(&(bar)[XB_TMO], 1u); break; } } } } while (0)
; DI void xcd_barrier(const XcdBarrier& b) {
;     ...
;         const unsigned old = xb_add(&bar[XB_XSUB(b.x)], 1u);
;         const unsigned gen = old / nloc;
;         if (old + 1u == (gen + 1u) * nloc) {
;             __builtin_amdgcn_fence(__ATOMIC_RELEASE, "agent");
;             asm volatile("s_waitcnt vmcnt(0)" ::: "memory");
;             const unsigned og = xb_add(&bar[XB_TOP], 1u);
;             const unsigned tg = og / nx;
;             if (og + 1u == (tg + 1u) * nx) xb_add(&bar[XB_TOPGEN], 1u);
;             else XB_SPIN(xb_ld(&bar[XB_TOPGEN]) == tg, bar);
;             __builtin_amdgcn_fence(__ATOMIC_ACQUIRE, "agent");
;             xb_add(&bar[XB_XGEN(b.x)], 1u);
.LBB0_1721:
	s_or_b64 exec, exec, s[4:5]
	s_waitcnt vmcnt(0)
	v_readfirstlane_b32 s2, v5
	v_sub_u32_e32 v6, 0, v4
	s_mov_b64 s[4:5], -1
	v_add_u32_e32 v5, s2, v3
	v_cvt_f32_u32_e32 v3, v4
	v_readlane_b32 s2, v253, 52
	v_readlane_b32 s3, v253, 53
	v_rcp_iflag_f32_e32 v3, v3
	s_nop 0
	v_mul_f32_e32 v3, 0x4f7ffffe, v3
	v_cvt_u32_f32_e32 v3, v3
	v_mul_lo_u32 v6, v6, v3
	v_mul_hi_u32 v6, v3, v6
	v_add_u32_e32 v3, v3, v6
	v_mul_hi_u32 v3, v5, v3
	v_mul_lo_u32 v6, v3, v4
	v_sub_u32_e32 v6, v5, v6
	v_cmp_ge_u32_e32 vcc, v6, v4
	v_add_u32_e32 v7, 1, v3
	v_add_u32_e32 v5, 1, v5
	v_cndmask_b32_e32 v3, v3, v7, vcc
	v_sub_u32_e32 v7, v6, v4
	v_cndmask_b32_e32 v6, v6, v7, vcc
	v_cmp_ge_u32_e32 vcc, v6, v4
	v_add_u32_e32 v6, 1, v3
	s_nop 0
	v_cndmask_b32_e32 v3, v3, v6, vcc
	v_mul_lo_u32 v6, v4, v3
	v_add_u32_e32 v4, v6, v4
	v_cmp_ne_u32_e32 vcc, v5, v4
	v_mov_b64_e32 v[4:5], s[2:3]
	s_cbranch_vccnz .Lxg_skip_8
	s_add_u32 s100, s74, 0x6400
	s_addc_u32 s101, s75, 0
	global_atomic_add v2, v197, s[100:101]
	global_atomic_add v2, v197, s[100:101] offset:256
	global_atomic_add v2, v197, s[100:101] offset:512
	global_atomic_add v2, v197, s[100:101] offset:768
	global_atomic_add v2, v197, s[100:101] offset:1024
	global_atomic_add v2, v197, s[100:101] offset:1280
	global_atomic_add v2, v197, s[100:101] offset:1536
	global_atomic_add v2, v197, s[100:101] offset:1792
	global_atomic_add v2, v197, s[100:101] offset:2048
	global_atomic_add v2, v197, s[100:101] offset:2304
	global_atomic_add v2, v197, s[100:101] offset:2560
	global_atomic_add v2, v197, s[100:101] offset:2816
	global_atomic_add v2, v197, s[100:101] offset:3072
	global_atomic_add v2, v197, s[100:101] offset:3328
	global_atomic_add v2, v197, s[100:101] offset:3584
	global_atomic_add v2, v197, s[100:101] offset:3840
.Lxg_skip_8:
	s_and_saveexec_b64 s[2:3], vcc
	s_cbranch_execz .LBB0_1733
	v_readlane_b32 s4, v253, 52
	v_readlane_b32 s5, v253, 53
	s_mov_b64 s[6:7], 0
	s_nop 3
	global_load_dword v4, v2, s[4:5] sc1
	s_waitcnt vmcnt(0)
	v_cmp_eq_u32_e32 vcc, v4, v3
	s_and_saveexec_b64 s[4:5], vcc
	s_cbranch_execz .LBB0_1732
	s_mov_b32 s16, 1
	s_branch .LBB0_1725

; DI unsigned xb_add(unsigned* p, unsigned v) { return __hip_atomic_fetch_add(p, v, __ATOMIC_RELAXED, __HIP_MEMORY_SCOPE_AGENT); }
; DI void xcd_barrier(const XcdBarrier& b) {
;     ...
;             __builtin_amdgcn_fence(__ATOMIC_ACQUIRE, "agent");
;             xb_add(&bar[XB_XGEN(b.x)], 1u);
;             asm volatile("s_waitcnt vmcnt(0)" ::: "memory");
.LBB0_1735:
	s_or_b64 exec, exec, s[2:3]
	s_mov_b64 s[2:3], exec
	v_mbcnt_lo_u32_b32 v3, s2, 0
	v_mbcnt_hi_u32_b32 v3, s3, v3
	v_cmp_eq_u32_e32 vcc, 0, v3
	s_waitcnt vmcnt(0)
	buffer_inv sc1
	s_and_saveexec_b64 s[4:5], vcc
	s_cbranch_execz .LBB0_1737
	s_bcnt1_i32_b64 s2, s[2:3]
	v_mov_b32_e32 v3, s2
	v_readlane_b32 s2, v253, 48
	v_readlane_b32 s3, v253, 49
	s_nop 4
	s_nop 0

; DI unsigned xb_add(unsigned* p, unsigned v) { return __hip_atomic_fetch_add(p, v, __ATOMIC_RELAXED, __HIP_MEMORY_SCOPE_AGENT); }
; DI void xcd_barrier(const XcdBarrier& b) {
;     ...
;             __builtin_amdgcn_fence(__ATOMIC_ACQUIRE, "agent");
;             xb_add(&bar[XB_XGEN(b.x)], 1u);
;             asm volatile("s_waitcnt vmcnt(0)" ::: "memory");
.LBB0_2487:
	s_bcnt1_i32_b64 s2, s[2:3]
	v_mov_b32_e32 v3, s2
	v_readlane_b32 s2, v253, 48
	v_readlane_b32 s3, v253, 49
	s_nop 4
	s_nop 0
	s_getpc_b64 s[98:99]
